# stick-breaking (D) early exit threshold -151 -> -135: remaining weights round to exactly 0 in the bf16 P operand; rest as v43
# speedup vs baseline: 1.0049x; 1.0022x over previous
; #define MFMA32(a, b, c) __builtin_amdgcn_mfma_f32_32x32x16_bf16((a), (b), (c), 0, 0, 0)
; template <int MODE>
; DI void attn_unit(unsigned char* lds, const AttnParams& ap, int b, int h, int qb, int tid) {
;     ...
; #pragma unroll
;       for (int kh = 0; kh < 2; ++kh)
; #pragma unroll
;         for (int kk = 0; kk < 2; ++kk) { const bf16x8 p0 = pack8(z[kh], kk);
; #pragma unroll
;           for (int eb = 0; eb < 2; ++eb) { const bf16_t* vb = Vs + (32 * eb + r32) * 72 + 32 * kh + 16 * kk + 8 * hi; const bf16x8 vf = *(const bf16x8*)vb;
;             O0[eb] = MFMA32(vf, p0, O0[eb]); } }
;       if (D_EARLY) { const int done = __all(cum <= -151.0f); if (lane == 0) flags[wave] = done; wdone = (done != 0); }
.LBB0_841:
	s_or_b64 exec, exec, s[86:87]
	ds_read_b128 v[34:37], v173 offset:9216
	v_cvt_pk_bf16_f32 v0, v0, v1
	v_cvt_pk_bf16_f32 v1, v2, v3
	v_cvt_pk_bf16_f32 v2, v4, v5
	v_cvt_pk_bf16_f32 v3, v6, v7
	ds_read_b128 v[4:7], v173 offset:13824
	v_sub_f32_e32 v172, v172, v192
	s_mov_b32 s8, 0xc3070000
	v_cmp_ge_f32_e64 s[8:9], s8, v172
	s_waitcnt lgkmcnt(1)
	v_mfma_f32_32x32x16_bf16 v[80:95], v[34:37], v[0:3], v[80:95]
	s_cmp_eq_u64 s[8:9], exec
	s_cselect_b64 s[8:9], -1, 0
	s_waitcnt lgkmcnt(0)
	v_mfma_f32_32x32x16_bf16 v[64:79], v[4:7], v[0:3], v[64:79]
	ds_read_b128 v[0:3], v173 offset:9248
	v_cvt_pk_bf16_f32 v4, v8, v9
	v_cvt_pk_bf16_f32 v5, v10, v11
	v_cvt_pk_bf16_f32 v6, v12, v13
	v_cvt_pk_bf16_f32 v7, v14, v15
	s_waitcnt lgkmcnt(0)
	s_nop 0
	v_mfma_f32_32x32x16_bf16 v[80:95], v[0:3], v[4:7], v[80:95]
	ds_read_b128 v[0:3], v173 offset:13856
	s_waitcnt lgkmcnt(0)
	v_mfma_f32_32x32x16_bf16 v[64:79], v[0:3], v[4:7], v[64:79]
	ds_read_b128 v[0:3], v173 offset:9280
	v_cvt_pk_bf16_f32 v4, v16, v17
	v_cvt_pk_bf16_f32 v5, v18, v19
	v_cvt_pk_bf16_f32 v6, v20, v21
	v_cvt_pk_bf16_f32 v7, v22, v23
	s_waitcnt lgkmcnt(0)
	s_nop 0
	v_mfma_f32_32x32x16_bf16 v[80:95], v[0:3], v[4:7], v[80:95]
	ds_read_b128 v[0:3], v173 offset:13888
	s_waitcnt lgkmcnt(0)
	v_mfma_f32_32x32x16_bf16 v[64:79], v[0:3], v[4:7], v[64:79]
	ds_read_b128 v[0:3], v173 offset:9312
	v_cvt_pk_bf16_f32 v4, v24, v25
	v_cvt_pk_bf16_f32 v5, v26, v27
	v_cvt_pk_bf16_f32 v6, v28, v29
	v_cvt_pk_bf16_f32 v7, v30, v31
	s_waitcnt lgkmcnt(0)
	s_nop 0
	v_mfma_f32_32x32x16_bf16 v[80:95], v[0:3], v[4:7], v[80:95]
	ds_read_b128 v[0:3], v173 offset:13920
	s_waitcnt lgkmcnt(0)
	v_mfma_f32_32x32x16_bf16 v[64:79], v[0:3], v[4:7], v[64:79]
	s_and_saveexec_b64 s[10:11], s[6:7]
	s_cbranch_execz .LBB0_830
	v_cndmask_b32_e64 v0, 0, 1, s[8:9]
	flat_store_dword v[162:163], v0 sc0 sc1
	s_waitcnt vmcnt(0)
	s_branch .LBB0_830
